# DeltaNet step D: the state-decay multiplies S*=exp(g_last) hoisted from between the state-update MFMAs to early in the step (right after the packed copy of S is taken); same ops, no VALU->MFMA accumul
# baseline (speedup 1.0000x reference)
.LBB0_705:
	v_mov_b32_e32 v0, s60
	v_cndmask_b32_e64 v155, v111, v0, s[6:7]
	s_add_i32 s18, 16, 0x21000
	s_add_i32 s19, 16, 0x8800
	v_mov_b32_e32 v3, v120
	v_mov_b32_e32 v0, v107
	v_mov_b32_e32 v74, v121
	s_and_b64 s[0:1], s[14:15], exec
	s_waitcnt lgkmcnt(0)
	s_barrier
	s_cselect_b32 s0, s19, s18
	v_mul_lo_u32 v0, v3, s24
	s_add_i32 s1, 16, 0x16400
	v_lshlrev_b32_e32 v68, 3, v74
	v_add3_u32 v0, s1, v0, v68
	v_add_u32_e32 v1, 0x1000, v0
	v_mul_lo_u32 v69, v3, 40
	v_lshl_add_u32 v3, v3, 1, s43
	v_mul_lo_u32 v74, v74, s25
	ds_read_b64 v[64:65], v1 offset:512
	ds_read_b64 v[66:67], v1 offset:544
	v_add_u32_e32 v1, 0x1800, v0
	v_add3_u32 v68, s40, v68, v69
	v_add_u32_e32 v156, v3, v74
	ds_read_b64 v[72:73], v0 offset:2304
	ds_read_b64 v[60:61], v1 offset:768
	ds_read_b64 v[62:63], v1 offset:800
	ds_read_b64 v[0:1], v0 offset:6976
	ds_read_b64 v[84:85], v68
	ds_read_b64 v[86:87], v68 offset:640
	ds_read_b64 v[70:71], v68 offset:1920
	ds_read_b64 v[68:69], v68 offset:1280
	ds_read_u16 v188, v156 offset:61696
	v_add_u32_e32 v75, 0xd000, v3
	v_add_u32_e32 v101, 0x6510, v74
	v_add_u32_e32 v162, v75, v101
	ds_read_u16 v77, v162
	ds_read_u16 v189, v156 offset:62224
	v_add_u32_e32 v102, 0x6720, v74
	v_add_u32_e32 v163, v75, v102
	ds_read_u16 v78, v163
	v_add_u32_e32 v100, 0x6300, v74
	ds_read_u16 v190, v156 offset:62752
	v_add_u32_e32 v96, 0x4200, v74
	v_add_u32_e32 v97, 0x4410, v74
	v_add_u32_e32 v98, 0x4620, v74
	v_add_u32_e32 v99, 0x4830, v74
	v_add_u32_e32 v74, 0x6930, v74
	v_add_u32_e32 v164, v75, v74
	v_add_u32_e32 v157, v75, v96
	v_add_u32_e32 v158, v75, v97
	v_add_u32_e32 v159, v75, v98
	v_add_u32_e32 v160, v75, v99
	v_add_u32_e32 v161, v75, v100
	ds_read_u16 v192, v164
	ds_read_u16 v191, v156 offset:63280
	v_add_u32_e32 v75, 0xd020, v3
	ds_read_u16 v193, v157
	v_add_u32_e32 v181, v75, v97
	v_add_u32_e32 v185, v75, v101
	v_add_u32_e32 v182, v75, v98
	v_add_u32_e32 v186, v75, v102
	ds_read_u16 v194, v158
	v_add_u32_e32 v180, v75, v96
	v_add_u32_e32 v183, v75, v99
	v_add_u32_e32 v184, v75, v100
	v_add_u32_e32 v187, v75, v74
	ds_read_u16 v195, v159
	ds_read_u16 v196, v160
	ds_read_u16 v76, v161
	s_waitcnt lgkmcnt(1)
	v_lshlrev_b32_e32 v88, 16, v188
	v_lshlrev_b32_e32 v89, 16, v189
	v_lshlrev_b32_e32 v90, 16, v190
	v_lshlrev_b32_e32 v77, 16, v77
	v_lshlrev_b32_e32 v78, 16, v78
	v_lshlrev_b32_e32 v79, 16, v192
	v_lshlrev_b32_e32 v91, 16, v191
	v_lshlrev_b32_e32 v80, 16, v193
	v_lshlrev_b32_e32 v81, 16, v194
	v_lshlrev_b32_e32 v82, 16, v195
	v_lshlrev_b32_e32 v83, 16, v196
	ds_read_u16 v168, v156 offset:53248
	ds_read_u16 v3, v156 offset:53280
	ds_read_u16 v92, v156 offset:53808
	ds_read_u16 v93, v156 offset:62256
	ds_read_u16 v97, v181
	ds_read_u16 v101, v185
	ds_read_u16 v94, v156 offset:62784
	ds_read_u16 v98, v182
	ds_read_u16 v102, v186
	s_waitcnt lgkmcnt(6)
	v_lshlrev_b32_e32 v165, 16, v92
	ds_read_u16 v92, v156 offset:54336
	ds_read_u16 v95, v156 offset:63312
	ds_read_u16 v99, v183
	ds_read_u16 v74, v187
	ds_read_u16 v96, v180
	ds_read_u16 v100, v184
	s_waitcnt lgkmcnt(5)
	v_lshlrev_b32_e32 v166, 16, v92
	ds_read_u16 v92, v156 offset:54864
	v_lshlrev_b32_e32 v3, 16, v3
	v_lshlrev_b32_e32 v76, 16, v76
	v_lshlrev_b32_e32 v93, 16, v93
	v_lshlrev_b32_e32 v94, 16, v94
	s_waitcnt lgkmcnt(0)
	v_lshlrev_b32_e32 v167, 16, v92
	ds_read_u16 v92, v156 offset:61728
	ds_read_u16 v169, v156 offset:54832
	ds_read_u16 v170, v156 offset:53776
	ds_read_u16 v171, v156 offset:54304
	v_lshlrev_b32_e32 v95, 16, v95
	v_lshlrev_b32_e32 v96, 16, v96
	v_lshlrev_b32_e32 v97, 16, v97
	s_waitcnt lgkmcnt(3)
	v_lshlrev_b32_e32 v92, 16, v92
	v_lshlrev_b32_e32 v98, 16, v98
	v_lshlrev_b32_e32 v99, 16, v99
	v_lshlrev_b32_e32 v100, 16, v100
	v_lshlrev_b32_e32 v101, 16, v101
	v_lshlrev_b32_e32 v102, 16, v102
	v_lshlrev_b32_e32 v103, 16, v74
	v_mov_b32_e32 v140, v84
	v_mov_b32_e32 v141, v85
	v_mov_b32_e32 v142, v2
	v_mov_b32_e32 v143, v2
	s_waitcnt lgkmcnt(2)
	v_lshlrev_b32_e32 v84, 16, v169
	v_lshlrev_b32_e32 v85, 16, v168
	s_waitcnt lgkmcnt(1)
	v_lshlrev_b32_e32 v168, 16, v170
	s_waitcnt lgkmcnt(0)
	v_lshlrev_b32_e32 v169, 16, v171
	v_cvt_pk_bf16_f32 v169, v169, v84
	v_cvt_pk_bf16_f32 v168, v85, v168
	v_mov_b32_e32 v170, v2
	v_mov_b32_e32 v171, v2
	v_mov_b32_e32 v74, v2
	v_mov_b32_e32 v75, v2
	v_mfma_f32_16x16x32_bf16 v[168:171], v[140:143], v[168:171], 0
	v_cvt_pk_bf16_f32 v173, v166, v167
	v_cvt_pk_bf16_f32 v172, v3, v165
	v_mov_b32_e32 v174, v2
	v_mov_b32_e32 v175, v2
	v_mov_b32_e32 v84, v86
	v_mov_b32_e32 v85, v87
	v_mfma_f32_16x16x32_bf16 v[140:143], v[140:143], v[172:175], 0
	s_nop 0
	v_cvt_pk_bf16_f32 v173, v170, v171
	v_cvt_pk_bf16_f32 v172, v168, v169
	v_mov_b32_e32 v86, v2
	v_mov_b32_e32 v87, v2
	v_mfma_f32_16x16x32_bf16 v[88:91], v[72:75], v[172:175], v[88:91]
	v_mov_b32_e32 v176, v2
	v_mov_b32_e32 v177, v2
	v_mov_b32_e32 v178, v2
	v_mov_b32_e32 v179, v2
	v_mov_b32_e32 v3, v2
	s_nop 2
	v_cvt_pk_bf16_f32 v175, v90, v91
	v_cvt_pk_bf16_f32 v174, v88, v89
	s_cmp_lg_u32 16, -1
	s_cselect_b32 s1, s41, 0
	v_mfma_f32_16x16x32_bf16 v[88:91], v[84:87], v[174:177], 0
	v_cvt_pk_bf16_f32 v177, v142, v143
	v_cvt_pk_bf16_f32 v176, v140, v141
	s_nop 1
	v_mfma_f32_16x16x32_bf16 v[72:75], v[72:75], v[176:179], v[92:95]
	s_nop 2
	v_cvt_pk_bf16_f32 v175, v90, v91
	v_cvt_pk_bf16_f32 v174, v88, v89
	v_mov_b32_e32 v94, v2
	v_mov_b32_e32 v95, v2
	s_nop 0
	v_cvt_pk_bf16_f32 v93, v74, v75
	v_cvt_pk_bf16_f32 v92, v72, v73
	v_mfma_f32_16x16x32_bf16 v[80:83], v[64:67], v[172:175], v[80:83]
	s_nop 0
	v_mfma_f32_16x16x32_bf16 v[72:75], v[84:87], v[92:95], 0
	v_mov_b32_e32 v84, v68
	v_mov_b32_e32 v85, v69
	s_nop 3
	v_cvt_pk_bf16_f32 v93, v82, v83
	v_cvt_pk_bf16_f32 v92, v80, v81
	v_mfma_f32_16x16x32_bf16 v[76:79], v[60:63], v[172:175], v[76:79]
	v_cvt_pk_bf16_f32 v179, v74, v75
	v_cvt_pk_bf16_f32 v178, v72, v73
	v_mov_b32_e32 v68, v2
	v_mfma_f32_16x16x32_bf16 v[80:83], v[84:87], v[92:95], 0
	v_mov_b32_e32 v69, v2
	v_mfma_f32_16x16x32_bf16 v[64:67], v[64:67], v[176:179], v[96:99]
	v_mfma_f32_16x16x32_bf16 v[60:63], v[60:63], v[176:179], v[100:103]
	s_nop 6
	v_cvt_pk_bf16_f32 v67, v66, v67
	v_cvt_pk_bf16_f32 v66, v64, v65
	s_nop 1
	v_mfma_f32_16x16x32_bf16 v[64:67], v[84:87], v[66:69], 0
	v_cvt_pk_bf16_f32 v85, v82, v83
	v_cvt_pk_bf16_f32 v84, v80, v81
	v_mov_b32_e32 v68, v70
	v_mov_b32_e32 v69, v71
	v_mov_b32_e32 v70, v2
	v_mov_b32_e32 v71, v2
	v_mfma_f32_16x16x32_bf16 v[76:79], v[0:3], v[84:87], v[76:79]
	s_nop 7
	v_cvt_pk_bf16_f32 v85, v78, v79
	v_cvt_pk_bf16_f32 v84, v76, v77
	s_nop 1
	v_mfma_f32_16x16x32_bf16 v[76:79], v[68:71], v[84:87], 0
	v_cvt_pk_bf16_f32 v85, v66, v67
	v_cvt_pk_bf16_f32 v84, v64, v65
	s_nop 1
	v_mfma_f32_16x16x32_bf16 v[60:63], v[0:3], v[84:87], v[60:63]
	v_cvt_pk_bf16_f32 v87, v30, v31
	v_cvt_pk_bf16_f32 v86, v28, v29
	v_cvt_pk_bf16_f32 v85, v34, v35
	v_cvt_pk_bf16_f32 v84, v32, v33
	s_nop 3
	v_cvt_pk_bf16_f32 v1, v62, v63
	v_cvt_pk_bf16_f32 v0, v60, v61
	s_nop 1
	v_mfma_f32_16x16x32_bf16 v[60:63], v[68:71], v[0:3], 0
	v_cvt_pk_bf16_f32 v0, v168, s0
	ds_write_b16 v156, v0 offset:53248
	v_cvt_pk_bf16_f32 v0, v169, s0
	ds_write_b16 v156, v0 offset:53776
	v_cvt_pk_bf16_f32 v0, v170, s0
	ds_write_b16 v156, v0 offset:54304
	v_cvt_pk_bf16_f32 v0, v171, s0
	ds_write_b16 v156, v0 offset:54832
	v_cvt_pk_bf16_f32 v0, v88, s0
	ds_write_b16 v156, v0 offset:61696
	v_cvt_pk_bf16_f32 v0, v89, s0
	ds_write_b16 v156, v0 offset:62224
	v_cvt_pk_bf16_f32 v0, v90, s0
	ds_write_b16 v156, v0 offset:62752
	v_cvt_pk_bf16_f32 v0, v91, s0
	ds_write_b16 v156, v0 offset:63280
	v_cvt_pk_bf16_f32 v0, v80, s0
	ds_write_b16 v157, v0
	v_cvt_pk_bf16_f32 v0, v81, s0
	ds_write_b16 v158, v0
	v_cvt_pk_bf16_f32 v0, v82, s0
	ds_write_b16 v159, v0
	v_cvt_pk_bf16_f32 v0, v83, s0
	ds_write_b16 v160, v0
	v_cvt_pk_bf16_f32 v0, v76, s0
	ds_write_b16 v161, v0
	v_cvt_pk_bf16_f32 v0, v77, s0
	ds_write_b16 v162, v0
	v_cvt_pk_bf16_f32 v0, v78, s0
	ds_write_b16 v163, v0
	v_cvt_pk_bf16_f32 v0, v79, s0
	ds_write_b16 v164, v0
	v_cvt_pk_bf16_f32 v0, v140, s0
	ds_write_b16 v156, v0 offset:53280
	v_cvt_pk_bf16_f32 v0, v141, s0
	ds_write_b16 v156, v0 offset:53808
	v_cvt_pk_bf16_f32 v0, v142, s0
	ds_write_b16 v156, v0 offset:54336
	v_cvt_pk_bf16_f32 v0, v143, s0
	ds_write_b16 v156, v0 offset:54864
	v_cvt_pk_bf16_f32 v0, v72, s0
	ds_write_b16 v156, v0 offset:61728
	v_cvt_pk_bf16_f32 v0, v73, s0
	ds_write_b16 v156, v0 offset:62256
	v_cvt_pk_bf16_f32 v0, v74, s0
	ds_write_b16 v156, v0 offset:62784
	v_cvt_pk_bf16_f32 v0, v75, s0
	ds_write_b16 v156, v0 offset:63312
	v_cvt_pk_bf16_f32 v0, v64, s0
	ds_write_b16 v180, v0
	v_cvt_pk_bf16_f32 v0, v65, s0
	ds_write_b16 v181, v0
	v_cvt_pk_bf16_f32 v0, v66, s0
	ds_write_b16 v182, v0
	v_cvt_pk_bf16_f32 v0, v67, s0
	ds_write_b16 v183, v0
	v_cvt_pk_bf16_f32 v0, v60, s0
	ds_write_b16 v184, v0
	v_cvt_pk_bf16_f32 v0, v61, s0
	ds_write_b16 v185, v0
	v_cvt_pk_bf16_f32 v0, v62, s0
	ds_write_b16 v186, v0
	v_cvt_pk_bf16_f32 v0, v63, s0
	v_mov_b32_e32 v3, v107
	v_mov_b32_e32 v88, v120
	v_mov_b32_e32 v89, v121
	ds_write_b16 v187, v0
	s_waitcnt lgkmcnt(0)
	s_barrier
	v_cvt_pk_bf16_f32 v63, v6, v7
	v_mul_lo_u32 v0, v88, s22
	v_lshlrev_b32_e32 v90, 3, v89
	v_add3_u32 v164, 16, v0, v90
	v_add_u32_e32 v0, 0xd000, v164
	ds_read_b64 v[72:73], v0 offset:256
	ds_read_b64 v[74:75], v0 offset:288
	ds_read_b64 v[76:77], v0 offset:320
	ds_read_b64 v[78:79], v0 offset:352
	v_cvt_pk_bf16_f32 v62, v4, v5
	v_cvt_pk_bf16_f32 v61, v10, v11
	v_cvt_pk_bf16_f32 v60, v8, v9
	ds_read_b64 v[80:81], v0 offset:384
	ds_read_b64 v[82:83], v0 offset:416
	v_cvt_pk_bf16_f32 v67, v14, v15
	s_waitcnt lgkmcnt(4)
	v_mfma_f32_16x16x32_bf16 v[72:75], v[72:75], v[60:63], 0
	v_cvt_pk_bf16_f32 v66, v12, v13
	v_cvt_pk_bf16_f32 v65, v18, v19
	v_cvt_pk_bf16_f32 v64, v16, v17
	ds_read_b64 v[92:93], v0 offset:448
	ds_read_b64 v[94:95], v0 offset:480
	v_mul_lo_u32 v0, v88, s21
	s_waitcnt lgkmcnt(4)
	v_mfma_f32_16x16x32_bf16 v[72:75], v[76:79], v[64:67], v[72:75]
	v_cvt_pk_bf16_f32 v71, v22, v23
	v_cvt_pk_bf16_f32 v70, v20, v21
	v_cvt_pk_bf16_f32 v69, v26, v27
	v_cvt_pk_bf16_f32 v68, v24, v25
	v_add3_u32 v165, s66, v90, v0
	ds_read_b64 v[76:77], v165
	ds_read_b64 v[78:79], v165 offset:32
	s_waitcnt lgkmcnt(4)
	v_mfma_f32_16x16x32_bf16 v[72:75], v[80:83], v[68:71], v[72:75]
	v_add_u32_e32 v1, 0xf000, v164
	ds_read_b64 v[98:99], v1 offset:640
	ds_read_b64 v[100:101], v1 offset:672
	v_add_u32_e32 v91, 0x1000, v165
	s_waitcnt lgkmcnt(4)
	v_mfma_f32_16x16x32_bf16 v[80:83], v[92:95], v[84:87], v[72:75]
	ds_read_b64 v[92:93], v165 offset:128
	ds_read_b64 v[94:95], v165 offset:160
	v_lshl_add_u32 v0, v88, 1, s61
	v_mad_u64_u32 v[102:103], s[12:13], v89, s25, v[0:1]
	ds_read_b64 v[72:73], v165 offset:64
	ds_read_b64 v[74:75], v165 offset:96
	s_waitcnt lgkmcnt(6)
	v_mfma_f32_16x16x32_bf16 v[76:79], v[76:79], v[60:63], 0
	s_waitcnt lgkmcnt(0)
	v_mfma_f32_16x16x32_bf16 v[72:75], v[72:75], v[64:67], v[76:79]
	s_nop 5
	ds_read_b64 v[76:77], v165 offset:192
	ds_read_b64 v[78:79], v165 offset:224
	v_mfma_f32_16x16x32_bf16 v[72:75], v[92:95], v[68:71], v[72:75]
	ds_read_b64 v[94:95], v1 offset:512
	ds_read_b64 v[96:97], v1 offset:544
	v_lshlrev_b32_e32 v92, 2, v89
	v_or_b32_e32 v176, 1, v92
	s_waitcnt lgkmcnt(2)
	v_mfma_f32_16x16x32_bf16 v[72:75], v[76:79], v[84:87], v[72:75]
	ds_read_b64 v[76:77], v1 offset:576
	ds_read_b64 v[78:79], v1 offset:608
	v_mad_u64_u32 v[160:161], s[12:13], v176, s22, v[0:1]
	s_waitcnt lgkmcnt(2)
	v_mfma_f32_16x16x32_bf16 v[94:97], v[94:97], v[60:63], 0
	v_add_u32_e32 v172, 0x1ef0, v160
	s_cselect_b32 s12, 16, 0
	s_add_u32 s12, s12, 0x1c8fc
	s_waitcnt lgkmcnt(0)
	v_mfma_f32_16x16x32_bf16 v[76:79], v[76:79], v[64:67], v[94:97]
	s_addc_u32 s13, s1, 0
	s_nop 1
	ds_read_b64 v[94:95], v91 offset:256
	ds_read_b64 v[96:97], v91 offset:288
	s_cmp_lg_u64 s[12:13], 0
	v_mfma_f32_16x16x32_bf16 v[76:79], v[98:101], v[68:71], v[76:79]
	ds_read_b64 v[98:99], v1 offset:704
	ds_read_b64 v[100:101], v1 offset:736
	ds_read_u16 v0, v102 offset:53248
	ds_read_u16 v1, v160 offset:53248
	ds_read_u16 v93, v160 offset:53776
	ds_read_u16 v102, v160 offset:54304
	ds_read_u16 v161, v160 offset:61168
	ds_read_u16 v162, v160 offset:61696
	ds_read_u16 v166, v160 offset:62224
	ds_read_u16 v167, v160 offset:62752
	ds_read_b64 v[140:141], v91 offset:320
	ds_read_b64 v[142:143], v91 offset:352
	s_waitcnt lgkmcnt(8)
	v_lshlrev_b32_e32 v1, 16, v1
	v_mfma_f32_16x16x32_bf16 v[94:97], v[94:97], v[60:63], 0
	v_lshlrev_b32_e32 v0, 16, v0
	v_pk_add_f32 v[0:1], v[0:1], v[80:81] neg_lo:[0,1] neg_hi:[0,1]
	v_add_u32_e32 v80, 0x4200, v164
	v_mfma_f32_16x16x32_bf16 v[98:101], v[98:101], v[84:87], v[76:79]
	v_add_u32_e32 v168, 0xd000, v80
	s_waitcnt lgkmcnt(6)
	v_lshlrev_b32_e32 v81, 16, v102
	ds_read_b64 v[156:157], v91 offset:448
	ds_read_b64 v[158:159], v91 offset:480
	ds_read_b64 v[76:77], v91 offset:384
	ds_read_b64 v[78:79], v91 offset:416
	s_waitcnt lgkmcnt(4)
	v_mfma_f32_16x16x32_bf16 v[94:97], v[140:143], v[64:67], v[94:97]
	ds_read_b64 v[140:141], v168 offset:256
	ds_read_b64 v[142:143], v168 offset:288
	v_lshlrev_b32_e32 v80, 16, v93
	v_pk_add_f32 v[102:103], v[80:81], v[82:83] neg_lo:[0,1] neg_hi:[0,1]
	ds_read_b64 v[80:81], v168 offset:320
	ds_read_b64 v[82:83], v168 offset:352
	s_waitcnt lgkmcnt(4)
	v_mfma_f32_16x16x32_bf16 v[76:79], v[76:79], v[68:71], v[94:97]
	s_nop 2
	ds_read_b64 v[94:95], v168 offset:384
	ds_read_b64 v[96:97], v168 offset:416
	v_add_u32_e32 v93, 0x2000, v165
	v_lshlrev_b32_e32 v163, 16, v162
	s_waitcnt lgkmcnt(4)
	v_mfma_f32_16x16x32_bf16 v[140:143], v[140:143], v[60:63], 0
	v_lshlrev_b32_e32 v162, 16, v161
	v_add_u32_e32 v165, 0x3000, v165
	s_cselect_b32 s1, s12, -1
	v_mfma_f32_16x16x32_bf16 v[76:79], v[156:159], v[84:87], v[76:79]
	ds_read_b64 v[156:157], v168 offset:448
	ds_read_b64 v[158:159], v168 offset:480
	v_pk_add_f32 v[168:169], v[162:163], v[98:99] neg_lo:[0,1] neg_hi:[0,1]
	v_lshlrev_b32_e32 v99, 16, v167
	s_waitcnt lgkmcnt(4)
	v_mfma_f32_16x16x32_bf16 v[80:83], v[80:83], v[64:67], v[140:143]
	v_lshlrev_b32_e32 v98, 16, v166
	v_pk_add_f32 v[170:171], v[98:99], v[100:101] neg_lo:[0,1] neg_hi:[0,1]
	ds_read_b64 v[98:99], v93 offset:704
	ds_read_b64 v[100:101], v93 offset:736
	ds_read_b64 v[140:141], v93 offset:512
	ds_read_b64 v[142:143], v93 offset:544
	s_waitcnt lgkmcnt(6)
	v_mfma_f32_16x16x32_bf16 v[80:83], v[94:97], v[68:71], v[80:83]
	ds_read_b64 v[94:95], v93 offset:576
	ds_read_b64 v[96:97], v93 offset:608
	s_add_i32 s66, 16, 0x258fc
	s_and_b64 s[12:13], s[14:15], exec
	s_waitcnt lgkmcnt(6)
	v_mfma_f32_16x16x32_bf16 v[156:159], v[156:159], v[84:87], v[80:83]
	s_cselect_b32 s1, s1, s66
	v_or_b32_e32 v177, 2, v92
	v_or_b32_e32 v178, 3, v92
	ds_read_b64 v[80:81], v93 offset:640
	ds_read_b64 v[82:83], v93 offset:672
	s_waitcnt lgkmcnt(4)
	v_mfma_f32_16x16x32_bf16 v[140:143], v[140:143], v[60:63], 0
	v_add_u32_e32 v91, 16, v92
	v_add_u32_e32 v179, 17, v92
	v_add_u32_e32 v180, 18, v92
	s_waitcnt lgkmcnt(2)
	v_mfma_f32_16x16x32_bf16 v[94:97], v[94:97], v[64:67], v[140:143]
	v_add_u32_e32 v181, 19, v92
	v_add_u32_e32 v93, 32, v92
	v_add_u32_e32 v182, 33, v92
	s_waitcnt lgkmcnt(0)
	v_mfma_f32_16x16x32_bf16 v[80:83], v[80:83], v[68:71], v[94:97]
	v_add_u32_e32 v140, 0x3ff0, v160
	v_add_u32_e32 v187, 34, v92
	v_add_u32_e32 v188, 35, v92
	v_add_u32_e32 v94, 0x6300, v164
	v_add_u32_e32 v162, 0xd000, v94
	ds_read_b64 v[94:95], v162 offset:256
	ds_read_b64 v[96:97], v162 offset:288
	ds_read_u16 v160, v172 offset:61696
	ds_read_u16 v141, v172 offset:62224
	ds_read_u16 v164, v172 offset:62752
	ds_read_u16 v166, v172 offset:63280
	ds_read_u16 v183, v140 offset:61696
	ds_read_u16 v184, v140 offset:62224
	ds_read_u16 v185, v140 offset:62752
	ds_read_u16 v186, v140 offset:63280
	s_waitcnt lgkmcnt(6)
	v_lshlrev_b32_e32 v161, 16, v141
	ds_read_b64 v[140:141], v162 offset:320
	ds_read_b64 v[142:143], v162 offset:352
	v_mfma_f32_16x16x32_bf16 v[80:83], v[98:101], v[84:87], v[80:83]
	ds_read_b64 v[98:99], v162 offset:384
	ds_read_b64 v[100:101], v162 offset:416
	v_lshlrev_b32_e32 v160, 16, v160
	v_pk_add_f32 v[172:173], v[160:161], v[156:157] neg_lo:[0,1] neg_hi:[0,1]
	v_mfma_f32_16x16x32_bf16 v[94:97], v[94:97], v[60:63], 0
	ds_read_b64 v[160:161], v162 offset:448
	ds_read_b64 v[162:163], v162 offset:480
	s_waitcnt lgkmcnt(10)
	v_lshlrev_b32_e32 v157, 16, v166
	v_lshlrev_b32_e32 v156, 16, v164
	s_waitcnt lgkmcnt(4)
	v_mfma_f32_16x16x32_bf16 v[94:97], v[140:143], v[64:67], v[94:97]
	ds_read_b64 v[140:141], v165 offset:768
	ds_read_b64 v[142:143], v165 offset:800
	v_pk_add_f32 v[174:175], v[156:157], v[158:159] neg_lo:[0,1] neg_hi:[0,1]
	v_add_u32_e32 v189, 49, v92
	s_waitcnt lgkmcnt(4)
	v_mfma_f32_16x16x32_bf16 v[94:97], v[98:101], v[68:71], v[94:97]
	ds_read_b64 v[98:99], v165 offset:832
	ds_read_b64 v[100:101], v165 offset:864
	s_add_i32 s60, s60, 1
	v_cmp_lt_u32_e32 vcc, s60, v109
	s_waitcnt lgkmcnt(2)
	v_mfma_f32_16x16x32_bf16 v[60:63], v[140:143], v[60:63], 0
	v_mfma_f32_16x16x32_bf16 v[156:159], v[160:163], v[84:87], v[94:97]
	ds_read_b64 v[160:161], v165 offset:896
	ds_read_b64 v[162:163], v165 offset:928
	ds_read_b64 v[166:167], v165 offset:992
	ds_read_b64 v[164:165], v165 offset:960
	s_nop 0
	v_lshlrev_b32_e32 v97, 16, v184
	s_waitcnt lgkmcnt(4)
	v_mfma_f32_16x16x32_bf16 v[60:63], v[98:101], v[64:67], v[60:63]
	v_lshlrev_b32_e32 v65, 16, v186
	v_lshlrev_b32_e32 v64, 16, v185
	v_lshlrev_b32_e32 v96, 16, v183
	s_waitcnt lgkmcnt(2)
	v_mfma_f32_16x16x32_bf16 v[60:63], v[160:163], v[68:71], v[60:63]
	v_add_f32_e64 v64, v64, -v158
	v_add_f32_e64 v65, v65, -v159
	v_mul_lo_u32 v159, v88, s24
	v_pk_add_f32 v[96:97], v[96:97], v[156:157] neg_lo:[0,1] neg_hi:[0,1]
	s_waitcnt lgkmcnt(0)
	v_mfma_f32_16x16x32_bf16 v[68:71], v[164:167], v[84:87], v[60:63]
	v_cvt_pk_bf16_f32 v66, v96, v97
	v_cvt_pk_bf16_f32 v67, v64, v65
	v_cvt_pk_bf16_f32 v65, v174, v175
	v_cvt_pk_bf16_f32 v60, v0, v1
	v_mov_b32_e32 v0, s1
	s_add_i32 s1, 16, 0x19200
	v_add_u32_e32 v158, s1, v90
	v_add_u32_e32 v84, v158, v159
	ds_read_b64 v[96:97], v84
	ds_read_b64 v[98:99], v84 offset:32
	ds_read_b32 v0, v0
	v_cvt_pk_bf16_f32 v61, v102, v103
	ds_read_b64 v[100:101], v84 offset:64
	ds_read_b64 v[102:103], v84 offset:96
	v_cvt_pk_bf16_f32 v63, v170, v171
	v_cvt_pk_bf16_f32 v62, v168, v169
	s_waitcnt lgkmcnt(2)
	v_mul_f32_e32 v157, 0x3fb8aa3b, v0
	v_exp_f32_e32 v196, v157
	s_nop 0
	v_pk_mul_f32 v[8:9], v[8:9], v[196:197] op_sel_hi:[1,0]
	v_pk_mul_f32 v[10:11], v[10:11], v[196:197] op_sel_hi:[1,0]
	v_pk_mul_f32 v[4:5], v[4:5], v[196:197] op_sel_hi:[1,0]
	v_pk_mul_f32 v[6:7], v[6:7], v[196:197] op_sel_hi:[1,0]
	v_pk_mul_f32 v[16:17], v[16:17], v[196:197] op_sel_hi:[1,0]
	v_pk_mul_f32 v[18:19], v[18:19], v[196:197] op_sel_hi:[1,0]
	v_pk_mul_f32 v[12:13], v[12:13], v[196:197] op_sel_hi:[1,0]
	v_pk_mul_f32 v[14:15], v[14:15], v[196:197] op_sel_hi:[1,0]
	v_pk_mul_f32 v[24:25], v[24:25], v[196:197] op_sel_hi:[1,0]
	v_pk_mul_f32 v[26:27], v[26:27], v[196:197] op_sel_hi:[1,0]
	v_pk_mul_f32 v[20:21], v[20:21], v[196:197] op_sel_hi:[1,0]
	v_mul_f32_e64 v22, v22, v196
	v_mul_f32_e64 v23, v23, v196
	v_pk_mul_f32 v[32:33], v[32:33], v[196:197] op_sel_hi:[1,0]
	v_pk_mul_f32 v[34:35], v[34:35], v[196:197] op_sel_hi:[1,0]
	v_pk_mul_f32 v[28:29], v[28:29], v[196:197] op_sel_hi:[1,0]
	v_pk_mul_f32 v[30:31], v[30:31], v[196:197] op_sel_hi:[1,0]
	v_lshlrev_b32_e32 v0, 6, v155
	v_lshl_add_u32 v155, v89, 4, s65
	ds_read_b128 v[140:143], v155
	v_ashrrev_i32_e32 v89, 31, v88
	v_lshl_add_u64 v[84:85], v[88:89], 2, v[116:117]
	v_mfma_f32_16x16x32_bf16 v[86:89], v[96:99], v[60:63], 0
	v_cvt_pk_bf16_f32 v64, v172, v173
	ds_read_b128 v[96:99], v155 offset:64
	s_waitcnt lgkmcnt(1)
	v_mul_f32_e32 v140, 0x3fb8aa3b, v140
	v_exp_f32_e32 v140, v140
	v_mfma_f32_16x16x32_bf16 v[86:89], v[100:103], v[64:67], v[86:89]
	v_sub_u32_e32 v100, 63, v92
	v_ashrrev_i32_e32 v1, 31, v0
	v_cndmask_b32_e64 v100, v100, v92, s[6:7]
	v_lshl_add_u64 v[0:1], v[0:1], 0, v[104:105]
	v_ashrrev_i32_e32 v101, 31, v100
	s_nop 2
	v_fma_f32 v72, v72, v140, v86
	v_lshl_add_u64 v[100:101], v[0:1], 0, v[100:101]
	v_mul_f32_e32 v86, 0x3fb8aa3b, v141
	v_lshlrev_b64 v[100:101], 12, v[100:101]
	v_exp_f32_e32 v86, v86
	v_lshl_add_u64 v[100:101], v[84:85], 0, v[100:101]
	global_store_dword v[100:101], v72, off
	v_sub_u32_e32 v72, 63, v176
	v_cndmask_b32_e64 v72, v72, v176, s[6:7]
	v_fma_f32 v86, v73, v86, v87
	v_ashrrev_i32_e32 v73, 31, v72
	v_lshl_add_u64 v[72:73], v[0:1], 0, v[72:73]
	v_lshlrev_b64 v[72:73], 12, v[72:73]
	v_lshl_add_u64 v[72:73], v[84:85], 0, v[72:73]
	v_mul_f32_e32 v87, 0x3fb8aa3b, v142
	global_store_dword v[72:73], v86, off
	v_sub_u32_e32 v72, 63, v177
	v_exp_f32_e32 v87, v87
	v_cndmask_b32_e64 v72, v72, v177, s[6:7]
	v_ashrrev_i32_e32 v73, 31, v72
	v_lshl_add_u64 v[72:73], v[0:1], 0, v[72:73]
	v_lshlrev_b64 v[72:73], 12, v[72:73]
	v_fma_f32 v74, v74, v87, v88
	v_lshl_add_u64 v[72:73], v[84:85], 0, v[72:73]
	v_add_u32_e32 v140, 0x900, v159
	global_store_dword v[72:73], v74, off
	v_mul_f32_e32 v72, 0x3fb8aa3b, v143
	v_add_u32_e32 v73, v158, v140
	v_exp_f32_e32 v72, v72
	ds_read_b64 v[100:101], v73
	ds_read_b64 v[102:103], v73 offset:32
	v_sub_u32_e32 v74, 63, v178
	v_cndmask_b32_e64 v86, v74, v178, s[6:7]
	v_fmac_f32_e32 v89, v75, v72
	ds_read_b64 v[74:75], v73 offset:96
	ds_read_b64 v[72:73], v73 offset:64
	v_ashrrev_i32_e32 v87, 31, v86
	v_lshl_add_u64 v[86:87], v[0:1], 0, v[86:87]
	s_waitcnt lgkmcnt(2)
	v_mfma_f32_16x16x32_bf16 v[100:103], v[100:103], v[60:63], 0
	v_lshlrev_b64 v[86:87], 12, v[86:87]
	v_lshl_add_u64 v[86:87], v[84:85], 0, v[86:87]
	global_store_dword v[86:87], v89, off
	v_mul_f32_e32 v86, 0x3fb8aa3b, v96
	v_exp_f32_e32 v87, v86
	s_waitcnt lgkmcnt(0)
	v_mfma_f32_16x16x32_bf16 v[72:75], v[72:75], v[64:67], v[100:103]
	v_sub_u32_e32 v86, 47, v92
	v_cndmask_b32_e64 v86, v86, v91, s[6:7]
	v_add_u32_e32 v141, 0x1200, v159
	ds_read_b128 v[100:103], v155 offset:128
	v_add_u32_e32 v94, 48, v92
	s_nop 2
	v_fma_f32 v72, v76, v87, v72
	v_ashrrev_i32_e32 v87, 31, v86
	v_lshl_add_u64 v[86:87], v[0:1], 0, v[86:87]
	v_mul_f32_e32 v76, 0x3fb8aa3b, v97
	v_lshlrev_b64 v[86:87], 12, v[86:87]
	v_exp_f32_e32 v76, v76
	v_lshl_add_u64 v[86:87], v[84:85], 0, v[86:87]
	global_store_dword v[86:87], v72, off
	v_sub_u32_e32 v72, 46, v92
	v_cndmask_b32_e64 v72, v72, v179, s[6:7]
	v_fma_f32 v76, v77, v76, v73
	v_ashrrev_i32_e32 v73, 31, v72
	v_lshl_add_u64 v[72:73], v[0:1], 0, v[72:73]
	v_lshlrev_b64 v[72:73], 12, v[72:73]
	v_lshl_add_u64 v[72:73], v[84:85], 0, v[72:73]
	v_mul_f32_e32 v77, 0x3fb8aa3b, v98
	global_store_dword v[72:73], v76, off
	v_sub_u32_e32 v72, 45, v92
	v_exp_f32_e32 v77, v77
	v_cndmask_b32_e64 v72, v72, v180, s[6:7]
	v_ashrrev_i32_e32 v73, 31, v72
	v_lshl_add_u64 v[72:73], v[0:1], 0, v[72:73]
	v_lshlrev_b64 v[72:73], 12, v[72:73]
	v_fma_f32 v74, v78, v77, v74
	v_lshl_add_u64 v[72:73], v[84:85], 0, v[72:73]
	global_store_dword v[72:73], v74, off
	v_add_u32_e32 v74, v158, v141
	v_mul_f32_e32 v73, 0x3fb8aa3b, v99
	ds_read_b64 v[86:87], v74
	ds_read_b64 v[88:89], v74 offset:32
	v_exp_f32_e32 v73, v73
	v_sub_u32_e32 v72, 44, v92
	v_cndmask_b32_e64 v72, v72, v181, s[6:7]
	ds_read_b64 v[96:97], v74 offset:64
	ds_read_b64 v[98:99], v74 offset:96
	v_fmac_f32_e32 v75, v79, v73
	v_ashrrev_i32_e32 v73, 31, v72
	v_lshl_add_u64 v[72:73], v[0:1], 0, v[72:73]
	v_lshlrev_b64 v[72:73], 12, v[72:73]
	v_lshl_add_u64 v[72:73], v[84:85], 0, v[72:73]
	global_store_dword v[72:73], v75, off
	s_waitcnt lgkmcnt(2)
	v_mfma_f32_16x16x32_bf16 v[72:75], v[86:89], v[60:63], 0
	ds_read_b128 v[76:79], v155 offset:192
	v_mul_f32_e32 v86, 0x3fb8aa3b, v100
	v_exp_f32_e32 v87, v86
	s_waitcnt lgkmcnt(1)
	v_mfma_f32_16x16x32_bf16 v[72:75], v[96:99], v[64:67], v[72:75]
	v_sub_u32_e32 v86, 31, v92
	v_cndmask_b32_e64 v86, v86, v93, s[6:7]
	v_add_u32_e32 v100, 0x1b00, v159
	v_add_u32_e32 v156, 50, v92
	v_add_u32_e32 v95, 51, v92
	s_nop 2
	v_fma_f32 v72, v80, v87, v72
	v_ashrrev_i32_e32 v87, 31, v86
	v_lshl_add_u64 v[86:87], v[0:1], 0, v[86:87]
	v_mul_f32_e32 v80, 0x3fb8aa3b, v101
	v_lshlrev_b64 v[86:87], 12, v[86:87]
	v_exp_f32_e32 v80, v80
	v_lshl_add_u64 v[86:87], v[84:85], 0, v[86:87]
	global_store_dword v[86:87], v72, off
	v_sub_u32_e32 v72, 30, v92
	v_cndmask_b32_e64 v72, v72, v182, s[6:7]
	v_fma_f32 v80, v81, v80, v73
	v_ashrrev_i32_e32 v73, 31, v72
	v_lshl_add_u64 v[72:73], v[0:1], 0, v[72:73]
	v_lshlrev_b64 v[72:73], 12, v[72:73]
	v_lshl_add_u64 v[72:73], v[84:85], 0, v[72:73]
	v_mul_f32_e32 v81, 0x3fb8aa3b, v102
	global_store_dword v[72:73], v80, off
	v_sub_u32_e32 v72, 29, v92
	v_exp_f32_e32 v81, v81
	v_cndmask_b32_e64 v72, v72, v187, s[6:7]
	v_ashrrev_i32_e32 v73, 31, v72
	v_lshl_add_u64 v[72:73], v[0:1], 0, v[72:73]
	v_lshlrev_b64 v[72:73], 12, v[72:73]
	v_fma_f32 v74, v82, v81, v74
	v_lshl_add_u64 v[72:73], v[84:85], 0, v[72:73]
	global_store_dword v[72:73], v74, off
	v_mul_f32_e32 v72, 0x3fb8aa3b, v103
	v_add_u32_e32 v74, v158, v100
	v_exp_f32_e32 v73, v72
	ds_read_b64 v[86:87], v74
	ds_read_b64 v[88:89], v74 offset:32
	v_sub_u32_e32 v72, 28, v92
	v_cndmask_b32_e64 v72, v72, v188, s[6:7]
	v_fmac_f32_e32 v75, v83, v73
	ds_read_b64 v[80:81], v74 offset:64
	ds_read_b64 v[82:83], v74 offset:96
	v_ashrrev_i32_e32 v73, 31, v72
	v_lshl_add_u64 v[72:73], v[0:1], 0, v[72:73]
	s_waitcnt lgkmcnt(2)
	v_mfma_f32_16x16x32_bf16 v[86:89], v[86:89], v[60:63], 0
	v_lshlrev_b64 v[72:73], 12, v[72:73]
	v_lshl_add_u64 v[72:73], v[84:85], 0, v[72:73]
	global_store_dword v[72:73], v75, off
	v_mul_f32_e32 v72, 0x3fb8aa3b, v76
	v_exp_f32_e32 v76, v72
	s_waitcnt lgkmcnt(0)
	v_mfma_f32_16x16x32_bf16 v[72:75], v[80:83], v[64:67], v[86:89]
	v_sub_u32_e32 v80, 15, v92
	v_cndmask_b32_e64 v80, v80, v94, s[6:7]
	v_ashrrev_i32_e32 v81, 31, v80
	v_lshl_add_u64 v[80:81], v[0:1], 0, v[80:81]
	v_lshlrev_b64 v[80:81], 12, v[80:81]
	s_nop 2
	v_fma_f32 v68, v68, v76, v72
	v_mul_f32_e32 v72, 0x3fb8aa3b, v77
	v_exp_f32_e32 v72, v72
	v_lshl_add_u64 v[80:81], v[84:85], 0, v[80:81]
	global_store_dword v[80:81], v68, off
	v_sub_u32_e32 v68, 14, v92
	v_cndmask_b32_e64 v68, v68, v189, s[6:7]
	v_fma_f32 v72, v69, v72, v73
	v_ashrrev_i32_e32 v69, 31, v68
	v_add_u32_e32 v101, s0, v159
	v_lshl_add_u64 v[68:69], v[0:1], 0, v[68:69]
	v_add_u32_e32 v73, v101, v90
	v_lshlrev_b64 v[68:69], 12, v[68:69]
	ds_read_b64 v[80:81], v73
	ds_read_b64 v[82:83], v73 offset:32
	v_lshl_add_u64 v[68:69], v[84:85], 0, v[68:69]
	global_store_dword v[68:69], v72, off
	v_sub_u32_e32 v69, 13, v92
	v_cndmask_b32_e64 v72, v69, v156, s[6:7]
	v_mul_f32_e32 v69, 0x3fb8aa3b, v78
	v_exp_f32_e32 v69, v69
	v_xor_b32_e32 v77, 8, v91
	v_fma_f32 v69, v70, v69, v74
	v_add_u32_e32 v70, s0, v141
	s_waitcnt lgkmcnt(0)
	v_mfma_f32_16x16x32_bf16 v[8:11], v[80:83], v[60:63], v[8:11]
	ds_read_b64 v[80:81], v73 offset:64
	ds_read_b64 v[82:83], v73 offset:96
	v_add_u32_e32 v73, s0, v140
	v_xad_u32 v76, v90, 16, v73
	v_lshl_add_u32 v77, v77, 1, v73
	ds_read_b64 v[86:87], v76
	ds_read_b64 v[88:89], v77
	v_xor_b32_e32 v76, 8, v93
	v_lshl_add_u32 v76, v76, 1, v73
	v_xor_b32_e32 v77, 8, v94
	v_lshl_add_u32 v73, v77, 1, v73
	ds_read_b64 v[96:97], v76
	ds_read_b64 v[98:99], v73
	v_xad_u32 v74, v90, 32, v70
	v_xor_b32_e32 v76, 16, v91
	s_waitcnt lgkmcnt(4)
	v_mfma_f32_16x16x32_bf16 v[8:11], v[80:83], v[64:67], v[8:11]
	v_lshl_add_u32 v76, v76, 1, v70
	ds_read_b64 v[80:81], v74
	ds_read_b64 v[82:83], v76
	v_xor_b32_e32 v74, 16, v93
	v_xor_b32_e32 v76, 16, v94
	v_lshl_add_u32 v74, v74, 1, v70
	v_lshl_add_u32 v70, v76, 1, v70
	s_waitcnt lgkmcnt(4)
	v_mfma_f32_16x16x32_bf16 v[4:7], v[86:89], v[60:63], v[4:7]
	v_ashrrev_i32_e32 v73, 31, v72
	ds_read_b64 v[86:87], v74
	ds_read_b64 v[88:89], v70
	v_add_u32_e32 v70, s0, v100
	v_lshl_add_u64 v[72:73], v[0:1], 0, v[72:73]
	v_xad_u32 v74, v90, 48, v70
	v_xor_b32_e32 v76, 24, v91
	v_lshlrev_b64 v[72:73], 12, v[72:73]
	s_waitcnt lgkmcnt(2)
	v_mfma_f32_16x16x32_bf16 v[16:19], v[80:83], v[60:63], v[16:19]
	v_lshl_add_u32 v76, v76, 1, v70
	ds_read_b64 v[80:81], v74
	ds_read_b64 v[82:83], v76
	v_xor_b32_e32 v74, 24, v93
	v_lshl_add_u32 v74, v74, 1, v70
	v_xor_b32_e32 v76, 24, v94
	v_lshl_add_u64 v[72:73], v[84:85], 0, v[72:73]
	v_mfma_f32_16x16x32_bf16 v[4:7], v[96:99], v[64:67], v[4:7]
	v_lshl_add_u32 v70, v76, 1, v70
	ds_read_b64 v[96:97], v74
	ds_read_b64 v[98:99], v70
	global_store_dword v[72:73], v69, off
	v_xad_u32 v72, v90, 64, v101
	v_xor_b32_e32 v73, 32, v91
	v_mul_f32_e32 v70, 0x3fb8aa3b, v79
	v_lshl_add_u32 v73, v73, 1, v101
	ds_read_b64 v[76:77], v72 offset:9216
	ds_read_b64 v[78:79], v73 offset:9216
	v_xor_b32_e32 v72, 32, v93
	v_xor_b32_e32 v73, 32, v94
	v_exp_f32_e32 v70, v70
	s_waitcnt lgkmcnt(4)
	v_mfma_f32_16x16x32_bf16 v[12:15], v[80:83], v[60:63], v[12:15]
	v_sub_u32_e32 v69, 12, v92
	v_lshl_add_u32 v72, v72, 1, v101
	v_lshl_add_u32 v73, v73, 1, v101
	s_movk_i32 s0, 0x50
	ds_read_b64 v[80:81], v72 offset:9216
	ds_read_b64 v[82:83], v73 offset:9216
	v_xad_u32 v72, v90, s0, v101
	v_xor_b32_e32 v73, 40, v91
	s_waitcnt lgkmcnt(2)
	v_mfma_f32_16x16x32_bf16 v[24:27], v[76:79], v[60:63], v[24:27]
	v_lshl_add_u32 v73, v73, 1, v101
	ds_read_b64 v[76:77], v72 offset:11520
	ds_read_b64 v[78:79], v73 offset:11520
	v_xor_b32_e32 v72, 40, v93
	v_lshl_add_u32 v72, v72, 1, v101
	v_xor_b32_e32 v73, 40, v94
	v_fmac_f32_e32 v75, v71, v70
	s_movk_i32 s0, 0x60
	v_xor_b32_e32 v70, 48, v91
	v_mfma_f32_16x16x32_bf16 v[16:19], v[86:89], v[64:67], v[16:19]
	v_lshl_add_u32 v73, v73, 1, v101
	ds_read_b64 v[86:87], v72 offset:11520
	ds_read_b64 v[88:89], v73 offset:11520
	v_mfma_f32_16x16x32_bf16 v[12:15], v[96:99], v[64:67], v[12:15]
	v_cndmask_b32_e64 v96, v69, v95, s[6:7]
	v_xad_u32 v69, v90, s0, v101
	v_lshl_add_u32 v72, v70, 1, v101
	ds_read_b64 v[70:71], v69 offset:13824
	ds_read_b64 v[72:73], v72 offset:13824
	v_xor_b32_e32 v69, 48, v93
	v_lshl_add_u32 v69, v69, 1, v101
	v_xor_b32_e32 v74, 48, v94
	s_waitcnt lgkmcnt(0)
	v_mfma_f32_16x16x32_bf16 v[32:35], v[70:73], v[60:63], v[32:35]
	s_movk_i32 s0, 0x70
	v_xor_b32_e32 v70, 56, v91
	v_lshl_add_u32 v74, v74, 1, v101
	v_mfma_f32_16x16x32_bf16 v[20:23], v[76:79], v[60:63], v[20:23]
	ds_read_b64 v[76:77], v69 offset:13824
	ds_read_b64 v[78:79], v74 offset:13824
	v_xad_u32 v69, v90, s0, v101
	v_lshl_add_u32 v72, v70, 1, v101
	ds_read_b64 v[70:71], v69 offset:16128
	ds_read_b64 v[72:73], v72 offset:16128
	v_xor_b32_e32 v69, 56, v93
	v_lshl_add_u32 v69, v69, 1, v101
	v_xor_b32_e32 v74, 56, v94
	v_mfma_f32_16x16x32_bf16 v[24:27], v[80:83], v[64:67], v[24:27]
	v_lshl_add_u32 v74, v74, 1, v101
	ds_read_b64 v[80:81], v69 offset:16128
	ds_read_b64 v[82:83], v74 offset:16128
	v_ashrrev_i32_e32 v97, 31, v96
	v_mfma_f32_16x16x32_bf16 v[20:23], v[86:89], v[64:67], v[20:23]
	v_lshl_add_u64 v[0:1], v[0:1], 0, v[96:97]
	v_lshlrev_b64 v[0:1], 12, v[0:1]
	v_lshl_add_u64 v[0:1], v[84:85], 0, v[0:1]
	s_waitcnt lgkmcnt(2)
	v_mfma_f32_16x16x32_bf16 v[28:31], v[70:73], v[60:63], v[28:31]
	global_store_dword v[0:1], v75, off
	v_mfma_f32_16x16x32_bf16 v[32:35], v[76:79], v[64:67], v[32:35]
	s_waitcnt lgkmcnt(0)
	v_mfma_f32_16x16x32_bf16 v[28:31], v[80:83], v[64:67], v[28:31]
	s_and_saveexec_b64 s[0:1], vcc
	s_cbranch_execz .LBB0_644
	v_and_b32_e32 v0, 7, v3
	v_ashrrev_i32_e32 v1, 3, v3
	v_cmp_eq_u32_e32 vcc, 0, v0
	s_and_saveexec_b64 s[12:13], vcc
	s_cbranch_execz .LBB0_643
	s_and_b64 s[66:67], s[14:15], exec
	s_cselect_b32 s66, s55, s64
	s_add_i32 s67, 16, 0x1c900
	s_add_i32 vcc_lo, 16, 0x25900
	s_and_b64 s[64:65], s[14:15], exec
	s_cselect_b32 s64, vcc_lo, s67
	v_lshlrev_b32_e32 v3, 2, v1
	v_add_u32_e32 v60, s64, v3
	v_add_u32_e32 v3, s66, v3
	s_waitcnt vmcnt(17)
	ds_write_b32 v3, v122
	ds_write_b32 v60, v110
	s_branch .LBB0_643
